# in-proj (EpiHyIn) epilogue: hoist all 16 rowss loads to top, remove 8 per-block vmcnt(0)
# baseline (speedup 1.0000x reference)
; __device__ __forceinline__ float ss_rinv(u64 v) { return __builtin_amdgcn_rsqf((float)v * SS_INV + 1e-6f); }
;     __device__ __forceinline__ void operator()(const f32x4 (&acc)[2][2][4][2], const pg8::Unit& u, int wr, int wc, int fr, int fq) const {
;     ...
;                 const int row0 = u.pm * 256 + ai * 128 + wr * 64 + m * 16;
;                 if (row0 >= MREAL) continue;
;                 const u64x2 s01 = *(const u64x2*)(rowss + row0 + 4 * fq), s23 = *(const u64x2*)(rowss + row0 + 4 * fq + 2);
;                 f32x4 ri; ri[0] = ss_rinv(s01[0]); ri[1] = ss_rinv(s01[1]); ri[2] = ss_rinv(s23[0]); ri[3] = ss_rinv(s23[1]);
;                 int s, p0, L; row_decode(row0, s, p0, L);
;                 const size_t so = seq_off_ch(s); const int LS = seq_LS(s);
.LBB0_1007:
	s_lshl_b32 s9, s16, 8
	s_add_i32 s16, s9, s41
	s_mov_b32 s17, 0
	v_lshl_add_u64 v[236:237], s[16:17], 3, v[144:145]
	global_load_dwordx4 v[166:169], v[236:237], off offset:16
	global_load_dwordx4 v[170:173], v[236:237], off
	global_load_dwordx4 v[174:177], v[236:237], off offset:144
	global_load_dwordx4 v[178:181], v[236:237], off offset:128
	global_load_dwordx4 v[182:185], v[236:237], off offset:272
	global_load_dwordx4 v[186:189], v[236:237], off offset:256
	global_load_dwordx4 v[190:193], v[236:237], off offset:400
	global_load_dwordx4 v[194:197], v[236:237], off offset:384
	global_load_dwordx4 v[198:201], v[236:237], off offset:1040
	global_load_dwordx4 v[216:219], v[236:237], off offset:1024
	global_load_dwordx4 v[220:223], v[236:237], off offset:1168
	global_load_dwordx4 v[224:227], v[236:237], off offset:1152
	global_load_dwordx4 v[228:231], v[236:237], off offset:1296
	global_load_dwordx4 v[232:235], v[236:237], off offset:1280
	global_load_dwordx4 v[146:149], v[236:237], off offset:1424
	global_load_dwordx4 v[236:239], v[236:237], off offset:1408
	s_waitcnt vmcnt(0)
	s_add_i32 s17, s16, 0xffff8000
	s_lshl_b32 s9, s18, 8
	s_lshr_b32 s23, s17, 12
	s_ashr_i32 s11, s18, 2
	s_and_b32 s9, s9, 0x300
	s_add_i32 s23, s23, 4
	s_ashr_i32 s22, s16, 13
	v_or_b32_e32 v164, s9, v162
	s_mul_hi_i32 s9, s11, 0xc300000
	s_mul_i32 s11, s11, 0xc300000
	s_cmp_gt_i32 s16, 0x1813f
	s_cbranch_scc1 .LBB0_1016
	s_ashr_i32 s17, s16, 31
	v_mov_b64_e32 v[130:131], v[166:167]
	v_mov_b64_e32 v[132:133], v[168:169]
	v_mov_b64_e32 v[134:135], v[170:171]
	v_mov_b64_e32 v[136:137], v[172:173]
	s_cmpk_gt_i32 s16, 0x7fff
	s_mov_b64 s[18:19], -1
	s_cbranch_scc0 .LBB0_1025
	s_cmp_gt_u32 s16, 0x17fff
	s_cbranch_scc0 .LBB0_1011
	s_add_i32 s17, s16, 0xfffe8000
	s_lshr_b32 s24, s17, 4
	s_mov_b64 s[18:19], 0

; __device__ __forceinline__ float ss_rinv(u64 v) { return __builtin_amdgcn_rsqf((float)v * SS_INV + 1e-6f); }
;     __device__ __forceinline__ void operator()(const f32x4 (&acc)[2][2][4][2], const pg8::Unit& u, int wr, int wc, int fr, int fq) const {
;     ...
;                 const int row0 = u.pm * 256 + ai * 128 + wr * 64 + m * 16;
;                 if (row0 >= MREAL) continue;
;                 const u64x2 s01 = *(const u64x2*)(rowss + row0 + 4 * fq), s23 = *(const u64x2*)(rowss + row0 + 4 * fq + 2);
;                 f32x4 ri; ri[0] = ss_rinv(s01[0]); ri[1] = ss_rinv(s01[1]); ri[2] = ss_rinv(s23[0]); ri[3] = ss_rinv(s23[1]);
.LBB0_1017:
	s_ashr_i32 s17, s16, 31
	v_mov_b64_e32 v[114:115], v[174:175]
	v_mov_b64_e32 v[116:117], v[176:177]
	v_mov_b64_e32 v[118:119], v[178:179]
	v_mov_b64_e32 v[120:121], v[180:181]
	s_cmp_lt_i32 s20, 0x8000
	s_mov_b64 s[18:19], -1
	s_cbranch_scc1 .LBB0_1039
	s_cmp_lt_u32 s16, 0x18000
	s_cbranch_scc1 .LBB0_1020
	s_add_i32 s17, s16, 0xfffe8010
	s_lshr_b32 s24, s17, 4
	s_mov_b64 s[18:19], 0

; __device__ __forceinline__ float ss_rinv(u64 v) { return __builtin_amdgcn_rsqf((float)v * SS_INV + 1e-6f); }
; __device__ __forceinline__ unsigned cvtpk(float lo, float hi) { f32x2 v = {lo, hi}; bf16x2_t b = __builtin_convertvector(v, bf16x2_t); return __builtin_bit_cast(unsigned, b); }
;     __device__ __forceinline__ void operator()(const f32x4 (&acc)[2][2][4][2], const pg8::Unit& u, int wr, int wc, int fr, int fq) const {
;     ...
;                 const u64x2 s01 = *(const u64x2*)(rowss + row0 + 4 * fq), s23 = *(const u64x2*)(rowss + row0 + 4 * fq + 2);
;                 f32x4 ri; ri[0] = ss_rinv(s01[0]); ri[1] = ss_rinv(s01[1]); ri[2] = ss_rinv(s23[0]); ri[3] = ss_rinv(s23[1]);
;                 int s, p0, L; row_decode(row0, s, p0, L);
;                 const size_t so = seq_off_ch(s); const int LS = seq_LS(s);
; #pragma unroll
;                 for (int bj = 0; bj < 2; ++bj)
; #pragma unroll
;                     for (int n = 0; n < 2; ++n) {
;                         const int col = u.pn * 256 + bj * 128 + wc * 32 + n * 16 + fr;
;                         const int part = col >> 10, ch = col & 1023;
;                         const f32x4 v = acc[ai][bj][m][n] * ri;
;                         u32x2 w; w.x = cvtpk(v[0], v[1]); w.y = cvtpk(v[2], v[3]);
;                         *(u32x2*)(XT + (size_t)part * REGION + so + (size_t)ch * LS + XPAD + p0 + 4 * fq) = w;
;                     }
.LBB0_1029:
	v_ffbh_u32_e32 v32, v135
	v_min_u32_e32 v32, 32, v32
	v_lshlrev_b64 v[134:135], v32, v[134:135]
	v_min_u32_e32 v134, 1, v134
	v_or_b32_e32 v134, v135, v134
	v_cvt_f32_u32_e32 v134, v134
	v_ffbh_u32_e32 v135, v137
	v_sub_u32_e32 v32, 32, v32
	v_min_u32_e32 v135, 32, v135
	v_ldexp_f32 v32, v134, v32
	v_fmamk_f32 v32, v32, 0x30800000, v203
	v_lshlrev_b64 v[136:137], v135, v[136:137]
	v_rsq_f32_e32 v134, v32
	v_min_u32_e32 v32, 1, v136
	v_ffbh_u32_e32 v136, v131
	v_min_u32_e32 v136, 32, v136
	v_lshlrev_b64 v[130:131], v136, v[130:131]
	v_min_u32_e32 v130, 1, v130
	v_or_b32_e32 v32, v137, v32
	v_or_b32_e32 v130, v131, v130
	v_cvt_f32_u32_e32 v32, v32
	v_cvt_f32_u32_e32 v130, v130
	v_sub_u32_e32 v135, 32, v135
	v_sub_u32_e32 v131, 32, v136
	v_ldexp_f32 v32, v32, v135
	v_ldexp_f32 v135, v130, v131
	v_ffbh_u32_e32 v130, v133
	v_min_u32_e32 v136, 32, v130
	v_lshlrev_b64 v[130:131], v136, v[132:133]
	v_min_u32_e32 v130, 1, v130
	v_or_b32_e32 v130, v131, v130
	v_cvt_f32_u32_e32 v131, v130
	v_sub_u32_e32 v132, 32, v136
	v_fmamk_f32 v32, v32, 0x30800000, v203
	v_fmamk_f32 v130, v135, 0x30800000, v203
	v_ldexp_f32 v131, v131, v132
	v_fmamk_f32 v131, v131, 0x30800000, v203
	v_rsq_f32_e32 v130, v130
	v_rsq_f32_e32 v131, v131
	v_rsq_f32_e32 v135, v32
	s_add_u32 s20, s39, s11
	s_addc_u32 s21, s40, s9
	s_lshl_b64 s[18:19], s[18:19], 1
	s_add_u32 s18, s20, s18
	v_mul_u32_u24_e32 v136, s17, v164
	v_pk_mul_f32 v[128:129], v[128:129], v[130:131]
	v_pk_mul_f32 v[126:127], v[126:127], v[134:135]
	s_addc_u32 s19, s21, s19
	v_lshlrev_b32_e32 v32, 1, v136
	v_cvt_pk_bf16_f32 v126, v126, v127
	v_cvt_pk_bf16_f32 v127, v128, v129
	v_lshl_add_u64 v[128:129], s[18:19], 0, v[32:33]
	s_lshl_b64 s[20:21], s[56:57], 1
	v_pk_mul_f32 v[124:125], v[124:125], v[130:131]
	v_pk_mul_f32 v[122:123], v[122:123], v[134:135]
	s_lshl_b32 s24, s17, 4
	s_lshl_b32 s56, s17, 5
	s_mulk_i32 s17, 0x70
	v_cvt_pk_bf16_f32 v122, v122, v123
	v_cvt_pk_bf16_f32 v123, v124, v125
	v_lshl_add_u64 v[124:125], v[128:129], 0, s[56:57]
	s_lshl_b32 s56, s17, 1
	s_add_i32 s17, s24, s17
	v_pk_mul_f32 v[116:117], v[116:117], v[130:131]
	v_pk_mul_f32 v[114:115], v[114:115], v[134:135]
	s_add_i32 s17, s17, s24
	v_lshl_add_u64 v[132:133], v[128:129], 0, s[20:21]
	v_lshlrev_b32_e32 v32, 1, v142
	v_pk_mul_f32 v[120:121], v[120:121], v[130:131]
	v_pk_mul_f32 v[118:119], v[118:119], v[134:135]
	v_cvt_pk_bf16_f32 v114, v114, v115
	v_cvt_pk_bf16_f32 v115, v116, v117
	v_add_lshl_u32 v116, s17, v136, 1
	v_mov_b32_e32 v117, v33
	v_lshl_add_u64 v[132:133], v[132:133], 0, v[32:33]
	v_cvt_pk_bf16_f32 v118, v118, v119
	v_cvt_pk_bf16_f32 v119, v120, v121
	v_lshl_add_u64 v[120:121], v[124:125], 0, s[56:57]
	v_lshl_add_u64 v[116:117], s[18:19], 0, v[116:117]
	global_store_dwordx2 v[132:133], v[126:127], off offset:96
	v_lshl_add_u64 v[126:127], v[124:125], 0, s[20:21]
	v_lshl_add_u64 v[120:121], v[120:121], 0, s[20:21]
	v_lshl_add_u64 v[116:117], v[116:117], 0, s[20:21]
	v_lshl_add_u64 v[126:127], v[126:127], 0, v[32:33]
	v_lshl_add_u64 v[120:121], v[120:121], 0, v[32:33]
	v_lshl_add_u64 v[116:117], v[116:117], 0, v[32:33]
	global_store_dwordx2 v[126:127], v[122:123], off offset:96
	global_store_dwordx2 v[120:121], v[118:119], off offset:96
	global_store_dwordx2 v[116:117], v[114:115], off offset:96
	s_or_b32 s20, s16, 16
	s_cmp_gt_i32 s20, 0x1813f
	s_cbranch_scc0 .LBB0_1017

; __device__ __forceinline__ float ss_rinv(u64 v) { return __builtin_amdgcn_rsqf((float)v * SS_INV + 1e-6f); }
;     __device__ __forceinline__ void operator()(const f32x4 (&acc)[2][2][4][2], const pg8::Unit& u, int wr, int wc, int fr, int fq) const {
;     ...
;                 const int row0 = u.pm * 256 + ai * 128 + wr * 64 + m * 16;
;                 if (row0 >= MREAL) continue;
;                 const u64x2 s01 = *(const u64x2*)(rowss + row0 + 4 * fq), s23 = *(const u64x2*)(rowss + row0 + 4 * fq + 2);
;                 f32x4 ri; ri[0] = ss_rinv(s01[0]); ri[1] = ss_rinv(s01[1]); ri[2] = ss_rinv(s23[0]); ri[3] = ss_rinv(s23[1]);
.LBB0_1031:
	s_ashr_i32 s17, s16, 31
	v_mov_b64_e32 v[98:99], v[182:183]
	v_mov_b64_e32 v[100:101], v[184:185]
	v_mov_b64_e32 v[102:103], v[186:187]
	v_mov_b64_e32 v[104:105], v[188:189]
	s_cmp_lt_i32 s20, 0x8000
	s_mov_b64 s[18:19], -1
	s_cbranch_scc1 .LBB0_1045
	s_cmp_lt_u32 s16, 0x18000
	s_cbranch_scc1 .LBB0_1034
	s_add_i32 s17, s16, 0xfffe8020
	s_lshr_b32 s24, s17, 4
	s_mov_b64 s[18:19], 0

; __device__ __forceinline__ float ss_rinv(u64 v) { return __builtin_amdgcn_rsqf((float)v * SS_INV + 1e-6f); }
; __device__ __forceinline__ unsigned cvtpk(float lo, float hi) { f32x2 v = {lo, hi}; bf16x2_t b = __builtin_convertvector(v, bf16x2_t); return __builtin_bit_cast(unsigned, b); }
;     __device__ __forceinline__ void operator()(const f32x4 (&acc)[2][2][4][2], const pg8::Unit& u, int wr, int wc, int fr, int fq) const {
;     ...
;                 const u64x2 s01 = *(const u64x2*)(rowss + row0 + 4 * fq), s23 = *(const u64x2*)(rowss + row0 + 4 * fq + 2);
;                 f32x4 ri; ri[0] = ss_rinv(s01[0]); ri[1] = ss_rinv(s01[1]); ri[2] = ss_rinv(s23[0]); ri[3] = ss_rinv(s23[1]);
;                 int s, p0, L; row_decode(row0, s, p0, L);
;                 const size_t so = seq_off_ch(s); const int LS = seq_LS(s);
; #pragma unroll
;                 for (int bj = 0; bj < 2; ++bj)
; #pragma unroll
;                     for (int n = 0; n < 2; ++n) {
;                         const int col = u.pn * 256 + bj * 128 + wc * 32 + n * 16 + fr;
;                         const int part = col >> 10, ch = col & 1023;
;                         const f32x4 v = acc[ai][bj][m][n] * ri;
;                         u32x2 w; w.x = cvtpk(v[0], v[1]); w.y = cvtpk(v[2], v[3]);
;                         *(u32x2*)(XT + (size_t)part * REGION + so + (size_t)ch * LS + XPAD + p0 + 4 * fq) = w;
;                     }
.LBB0_1043:
	v_ffbh_u32_e32 v32, v119
	v_min_u32_e32 v32, 32, v32
	v_lshlrev_b64 v[118:119], v32, v[118:119]
	v_min_u32_e32 v118, 1, v118
	v_or_b32_e32 v118, v119, v118
	v_cvt_f32_u32_e32 v118, v118
	v_ffbh_u32_e32 v119, v121
	v_sub_u32_e32 v32, 32, v32
	v_min_u32_e32 v119, 32, v119
	v_ldexp_f32 v32, v118, v32
	v_fmamk_f32 v32, v32, 0x30800000, v203
	v_lshlrev_b64 v[120:121], v119, v[120:121]
	v_rsq_f32_e32 v118, v32
	v_min_u32_e32 v32, 1, v120
	v_ffbh_u32_e32 v120, v115
	v_min_u32_e32 v120, 32, v120
	v_lshlrev_b64 v[114:115], v120, v[114:115]
	v_min_u32_e32 v114, 1, v114
	v_or_b32_e32 v32, v121, v32
	v_or_b32_e32 v114, v115, v114
	v_cvt_f32_u32_e32 v32, v32
	v_cvt_f32_u32_e32 v114, v114
	v_sub_u32_e32 v119, 32, v119
	v_sub_u32_e32 v115, 32, v120
	v_ldexp_f32 v32, v32, v119
	v_ldexp_f32 v119, v114, v115
	v_ffbh_u32_e32 v114, v117
	v_min_u32_e32 v120, 32, v114
	v_lshlrev_b64 v[114:115], v120, v[116:117]
	v_min_u32_e32 v114, 1, v114
	v_or_b32_e32 v114, v115, v114
	v_cvt_f32_u32_e32 v115, v114
	v_sub_u32_e32 v116, 32, v120
	v_fmamk_f32 v32, v32, 0x30800000, v203
	v_fmamk_f32 v114, v119, 0x30800000, v203
	v_ldexp_f32 v115, v115, v116
	v_fmamk_f32 v115, v115, 0x30800000, v203
	v_rsq_f32_e32 v114, v114
	v_rsq_f32_e32 v115, v115
	v_rsq_f32_e32 v119, v32
	s_add_u32 s20, s39, s11
	s_addc_u32 s21, s40, s9
	s_lshl_b64 s[18:19], s[18:19], 1
	s_add_u32 s18, s20, s18
	v_mul_u32_u24_e32 v120, s17, v164
	v_pk_mul_f32 v[112:113], v[112:113], v[114:115]
	v_pk_mul_f32 v[110:111], v[110:111], v[118:119]
	s_addc_u32 s19, s21, s19
	v_lshlrev_b32_e32 v32, 1, v120
	v_cvt_pk_bf16_f32 v110, v110, v111
	v_cvt_pk_bf16_f32 v111, v112, v113
	v_lshl_add_u64 v[112:113], s[18:19], 0, v[32:33]
	s_lshl_b64 s[20:21], s[56:57], 1
	v_pk_mul_f32 v[108:109], v[108:109], v[114:115]
	v_pk_mul_f32 v[106:107], v[106:107], v[118:119]
	s_lshl_b32 s24, s17, 4
	s_lshl_b32 s56, s17, 5
	s_mulk_i32 s17, 0x70
	v_cvt_pk_bf16_f32 v106, v106, v107
	v_cvt_pk_bf16_f32 v107, v108, v109
	v_lshl_add_u64 v[108:109], v[112:113], 0, s[56:57]
	s_lshl_b32 s56, s17, 1
	s_add_i32 s17, s24, s17
	v_pk_mul_f32 v[100:101], v[100:101], v[114:115]
	v_pk_mul_f32 v[98:99], v[98:99], v[118:119]
	s_add_i32 s17, s17, s24
	v_lshl_add_u64 v[116:117], v[112:113], 0, s[20:21]
	v_lshlrev_b32_e32 v32, 1, v142
	v_pk_mul_f32 v[104:105], v[104:105], v[114:115]
	v_pk_mul_f32 v[102:103], v[102:103], v[118:119]
	v_cvt_pk_bf16_f32 v98, v98, v99
	v_cvt_pk_bf16_f32 v99, v100, v101
	v_add_lshl_u32 v100, s17, v120, 1
	v_mov_b32_e32 v101, v33
	v_lshl_add_u64 v[116:117], v[116:117], 0, v[32:33]
	v_cvt_pk_bf16_f32 v102, v102, v103
	v_cvt_pk_bf16_f32 v103, v104, v105
	v_lshl_add_u64 v[104:105], v[108:109], 0, s[56:57]
	v_lshl_add_u64 v[100:101], s[18:19], 0, v[100:101]
	global_store_dwordx2 v[116:117], v[110:111], off offset:96
	v_lshl_add_u64 v[110:111], v[108:109], 0, s[20:21]
	v_lshl_add_u64 v[104:105], v[104:105], 0, s[20:21]
	v_lshl_add_u64 v[100:101], v[100:101], 0, s[20:21]
	v_lshl_add_u64 v[110:111], v[110:111], 0, v[32:33]
	v_lshl_add_u64 v[104:105], v[104:105], 0, v[32:33]
	v_lshl_add_u64 v[100:101], v[100:101], 0, v[32:33]
	global_store_dwordx2 v[110:111], v[106:107], off offset:96
	global_store_dwordx2 v[104:105], v[102:103], off offset:96
	global_store_dwordx2 v[100:101], v[98:99], off offset:96
	s_or_b32 s20, s16, 32
	s_cmp_gt_i32 s20, 0x1813f
	s_cbranch_scc0 .LBB0_1031

; __device__ __forceinline__ float ss_rinv(u64 v) { return __builtin_amdgcn_rsqf((float)v * SS_INV + 1e-6f); }
; __device__ __forceinline__ unsigned cvtpk(float lo, float hi) { f32x2 v = {lo, hi}; bf16x2_t b = __builtin_convertvector(v, bf16x2_t); return __builtin_bit_cast(unsigned, b); }
;     __device__ __forceinline__ void operator()(const f32x4 (&acc)[2][2][4][2], const pg8::Unit& u, int wr, int wc, int fr, int fq) const {
;     ...
;                 const int row0 = u.pm * 256 + ai * 128 + wr * 64 + m * 16;
;                 if (row0 >= MREAL) continue;
;                 const u64x2 s01 = *(const u64x2*)(rowss + row0 + 4 * fq), s23 = *(const u64x2*)(rowss + row0 + 4 * fq + 2);
;                 f32x4 ri; ri[0] = ss_rinv(s01[0]); ri[1] = ss_rinv(s01[1]); ri[2] = ss_rinv(s23[0]); ri[3] = ss_rinv(s23[1]);
;                 int s, p0, L; row_decode(row0, s, p0, L);
;                 const size_t so = seq_off_ch(s); const int LS = seq_LS(s);
; #pragma unroll
;                 for (int bj = 0; bj < 2; ++bj)
; #pragma unroll
;                     for (int n = 0; n < 2; ++n) {
;                         const int col = u.pn * 256 + bj * 128 + wc * 32 + n * 16 + fr;
;                         const int part = col >> 10, ch = col & 1023;
;                         const f32x4 v = acc[ai][bj][m][n] * ri;
;                         u32x2 w; w.x = cvtpk(v[0], v[1]); w.y = cvtpk(v[2], v[3]);
;                         *(u32x2*)(XT + (size_t)part * REGION + so + (size_t)ch * LS + XPAD + p0 + 4 * fq) = w;
;                     }
.LBB0_1049:
	v_ffbh_u32_e32 v32, v103
	v_min_u32_e32 v32, 32, v32
	v_lshlrev_b64 v[102:103], v32, v[102:103]
	v_min_u32_e32 v102, 1, v102
	v_or_b32_e32 v102, v103, v102
	v_cvt_f32_u32_e32 v102, v102
	v_ffbh_u32_e32 v103, v105
	v_sub_u32_e32 v32, 32, v32
	v_min_u32_e32 v103, 32, v103
	v_ldexp_f32 v32, v102, v32
	v_fmamk_f32 v32, v32, 0x30800000, v203
	v_lshlrev_b64 v[104:105], v103, v[104:105]
	v_rsq_f32_e32 v102, v32
	v_min_u32_e32 v32, 1, v104
	v_ffbh_u32_e32 v104, v99
	v_min_u32_e32 v104, 32, v104
	v_lshlrev_b64 v[98:99], v104, v[98:99]
	v_min_u32_e32 v98, 1, v98
	v_or_b32_e32 v32, v105, v32
	v_or_b32_e32 v98, v99, v98
	v_cvt_f32_u32_e32 v32, v32
	v_cvt_f32_u32_e32 v98, v98
	v_sub_u32_e32 v103, 32, v103
	v_sub_u32_e32 v99, 32, v104
	v_ldexp_f32 v32, v32, v103
	v_ldexp_f32 v103, v98, v99
	v_ffbh_u32_e32 v98, v101
	v_min_u32_e32 v104, 32, v98
	v_lshlrev_b64 v[98:99], v104, v[100:101]
	v_min_u32_e32 v98, 1, v98
	v_or_b32_e32 v98, v99, v98
	v_cvt_f32_u32_e32 v99, v98
	v_sub_u32_e32 v100, 32, v104
	v_fmamk_f32 v32, v32, 0x30800000, v203
	v_fmamk_f32 v98, v103, 0x30800000, v203
	v_ldexp_f32 v99, v99, v100
	v_fmamk_f32 v99, v99, 0x30800000, v203
	v_rsq_f32_e32 v98, v98
	v_rsq_f32_e32 v99, v99
	v_rsq_f32_e32 v103, v32
	s_add_u32 s20, s39, s11
	s_addc_u32 s21, s40, s9
	s_lshl_b64 s[18:19], s[18:19], 1
	s_add_u32 s18, s20, s18
	v_mul_u32_u24_e32 v104, s17, v164
	v_pk_mul_f32 v[96:97], v[96:97], v[98:99]
	v_pk_mul_f32 v[94:95], v[94:95], v[102:103]
	s_addc_u32 s19, s21, s19
	v_lshlrev_b32_e32 v32, 1, v104
	v_cvt_pk_bf16_f32 v94, v94, v95
	v_cvt_pk_bf16_f32 v95, v96, v97
	v_lshl_add_u64 v[96:97], s[18:19], 0, v[32:33]
	s_lshl_b64 s[20:21], s[56:57], 1
	v_pk_mul_f32 v[92:93], v[92:93], v[98:99]
	v_pk_mul_f32 v[90:91], v[90:91], v[102:103]
	s_lshl_b32 s24, s17, 4
	s_lshl_b32 s56, s17, 5
	s_mulk_i32 s17, 0x70
	v_cvt_pk_bf16_f32 v90, v90, v91
	v_cvt_pk_bf16_f32 v91, v92, v93
	v_lshl_add_u64 v[92:93], v[96:97], 0, s[56:57]
	s_lshl_b32 s56, s17, 1
	s_add_i32 s17, s24, s17
	v_pk_mul_f32 v[84:85], v[84:85], v[98:99]
	v_pk_mul_f32 v[82:83], v[82:83], v[102:103]
	s_add_i32 s17, s17, s24
	v_lshl_add_u64 v[100:101], v[96:97], 0, s[20:21]
	v_lshlrev_b32_e32 v32, 1, v142
	v_pk_mul_f32 v[88:89], v[88:89], v[98:99]
	v_pk_mul_f32 v[86:87], v[86:87], v[102:103]
	v_cvt_pk_bf16_f32 v82, v82, v83
	v_cvt_pk_bf16_f32 v83, v84, v85
	v_add_lshl_u32 v84, s17, v104, 1
	v_mov_b32_e32 v85, v33
	v_lshl_add_u64 v[100:101], v[100:101], 0, v[32:33]
	v_cvt_pk_bf16_f32 v86, v86, v87
	v_cvt_pk_bf16_f32 v87, v88, v89
	v_lshl_add_u64 v[88:89], v[92:93], 0, s[56:57]
	v_lshl_add_u64 v[84:85], s[18:19], 0, v[84:85]
	global_store_dwordx2 v[100:101], v[94:95], off offset:96
	v_lshl_add_u64 v[94:95], v[92:93], 0, s[20:21]
	v_lshl_add_u64 v[88:89], v[88:89], 0, s[20:21]
	v_lshl_add_u64 v[84:85], v[84:85], 0, s[20:21]
	v_lshl_add_u64 v[94:95], v[94:95], 0, v[32:33]
	v_lshl_add_u64 v[88:89], v[88:89], 0, v[32:33]
	v_lshl_add_u64 v[84:85], v[84:85], 0, v[32:33]
	global_store_dwordx2 v[94:95], v[90:91], off offset:96
	global_store_dwordx2 v[88:89], v[86:87], off offset:96
	global_store_dwordx2 v[84:85], v[82:83], off offset:96
	s_or_b32 s20, s16, 48
	s_cmp_gt_i32 s20, 0x1813f
	s_cbranch_scc1 .LBB0_1063
.LBB0_1050:
	s_ashr_i32 s17, s16, 31
	v_mov_b64_e32 v[82:83], v[190:191]
	v_mov_b64_e32 v[84:85], v[192:193]
	v_mov_b64_e32 v[86:87], v[194:195]
	v_mov_b64_e32 v[88:89], v[196:197]
	s_cmp_lt_i32 s20, 0x8000
	s_mov_b64 s[18:19], -1
	s_cbranch_scc1 .LBB0_1058
	s_cmp_lt_u32 s16, 0x18000
	s_cbranch_scc1 .LBB0_1053
	s_add_i32 s17, s16, 0xfffe8030
	s_lshr_b32 s24, s17, 4
	s_mov_b64 s[18:19], 0

; __device__ __forceinline__ float ss_rinv(u64 v) { return __builtin_amdgcn_rsqf((float)v * SS_INV + 1e-6f); }
; __device__ __forceinline__ unsigned cvtpk(float lo, float hi) { f32x2 v = {lo, hi}; bf16x2_t b = __builtin_convertvector(v, bf16x2_t); return __builtin_bit_cast(unsigned, b); }
;     __device__ __forceinline__ void operator()(const f32x4 (&acc)[2][2][4][2], const pg8::Unit& u, int wr, int wc, int fr, int fq) const {
;     ...
;                 const int row0 = u.pm * 256 + ai * 128 + wr * 64 + m * 16;
;                 if (row0 >= MREAL) continue;
;                 const u64x2 s01 = *(const u64x2*)(rowss + row0 + 4 * fq), s23 = *(const u64x2*)(rowss + row0 + 4 * fq + 2);
;                 f32x4 ri; ri[0] = ss_rinv(s01[0]); ri[1] = ss_rinv(s01[1]); ri[2] = ss_rinv(s23[0]); ri[3] = ss_rinv(s23[1]);
;                 int s, p0, L; row_decode(row0, s, p0, L);
;                 const size_t so = seq_off_ch(s); const int LS = seq_LS(s);
; #pragma unroll
;                 for (int bj = 0; bj < 2; ++bj)
; #pragma unroll
;                     for (int n = 0; n < 2; ++n) {
;                         const int col = u.pn * 256 + bj * 128 + wc * 32 + n * 16 + fr;
;                         const int part = col >> 10, ch = col & 1023;
;                         const f32x4 v = acc[ai][bj][m][n] * ri;
;                         u32x2 w; w.x = cvtpk(v[0], v[1]); w.y = cvtpk(v[2], v[3]);
;                         *(u32x2*)(XT + (size_t)part * REGION + so + (size_t)ch * LS + XPAD + p0 + 4 * fq) = w;
;                     }
.LBB0_1062:
	v_ffbh_u32_e32 v32, v87
	v_min_u32_e32 v32, 32, v32
	v_lshlrev_b64 v[86:87], v32, v[86:87]
	v_min_u32_e32 v86, 1, v86
	v_or_b32_e32 v86, v87, v86
	v_cvt_f32_u32_e32 v86, v86
	v_ffbh_u32_e32 v87, v89
	v_sub_u32_e32 v32, 32, v32
	v_min_u32_e32 v87, 32, v87
	v_ldexp_f32 v32, v86, v32
	v_fmamk_f32 v32, v32, 0x30800000, v203
	v_lshlrev_b64 v[88:89], v87, v[88:89]
	v_rsq_f32_e32 v86, v32
	v_min_u32_e32 v32, 1, v88
	v_ffbh_u32_e32 v88, v83
	v_min_u32_e32 v88, 32, v88
	v_lshlrev_b64 v[82:83], v88, v[82:83]
	v_min_u32_e32 v82, 1, v82
	v_or_b32_e32 v32, v89, v32
	v_or_b32_e32 v82, v83, v82
	v_cvt_f32_u32_e32 v32, v32
	v_cvt_f32_u32_e32 v82, v82
	v_sub_u32_e32 v87, 32, v87
	v_sub_u32_e32 v83, 32, v88
	v_ldexp_f32 v32, v32, v87
	v_ldexp_f32 v87, v82, v83
	v_ffbh_u32_e32 v82, v85
	v_min_u32_e32 v88, 32, v82
	v_lshlrev_b64 v[82:83], v88, v[84:85]
	v_min_u32_e32 v82, 1, v82
	v_or_b32_e32 v82, v83, v82
	v_cvt_f32_u32_e32 v83, v82
	v_sub_u32_e32 v84, 32, v88
	v_fmamk_f32 v32, v32, 0x30800000, v203
	v_fmamk_f32 v82, v87, 0x30800000, v203
	v_ldexp_f32 v83, v83, v84
	v_fmamk_f32 v83, v83, 0x30800000, v203
	v_rsq_f32_e32 v82, v82
	v_rsq_f32_e32 v83, v83
	v_rsq_f32_e32 v87, v32
	s_add_u32 s20, s39, s11
	s_addc_u32 s21, s40, s9
	s_lshl_b64 s[18:19], s[18:19], 1
	s_add_u32 s18, s20, s18
	v_mul_u32_u24_e32 v88, s17, v164
	v_pk_mul_f32 v[80:81], v[80:81], v[82:83]
	v_pk_mul_f32 v[78:79], v[78:79], v[86:87]
	s_addc_u32 s19, s21, s19
	v_lshlrev_b32_e32 v32, 1, v88
	v_cvt_pk_bf16_f32 v78, v78, v79
	v_cvt_pk_bf16_f32 v79, v80, v81
	v_lshl_add_u64 v[80:81], s[18:19], 0, v[32:33]
	s_lshl_b64 s[20:21], s[56:57], 1
	v_pk_mul_f32 v[76:77], v[76:77], v[82:83]
	v_pk_mul_f32 v[74:75], v[74:75], v[86:87]
	s_lshl_b32 s22, s17, 4
	s_lshl_b32 s56, s17, 5
	s_mulk_i32 s17, 0x70
	v_cvt_pk_bf16_f32 v74, v74, v75
	v_cvt_pk_bf16_f32 v75, v76, v77
	v_lshl_add_u64 v[76:77], v[80:81], 0, s[56:57]
	s_lshl_b32 s56, s17, 1
	s_add_i32 s17, s22, s17
	v_pk_mul_f32 v[68:69], v[68:69], v[82:83]
	v_pk_mul_f32 v[66:67], v[66:67], v[86:87]
	s_add_i32 s17, s17, s22
	v_lshl_add_u64 v[84:85], v[80:81], 0, s[20:21]
	v_lshlrev_b32_e32 v32, 1, v142
	v_pk_mul_f32 v[72:73], v[72:73], v[82:83]
	v_pk_mul_f32 v[70:71], v[70:71], v[86:87]
	v_cvt_pk_bf16_f32 v66, v66, v67
	v_cvt_pk_bf16_f32 v67, v68, v69
	v_add_lshl_u32 v68, s17, v88, 1
	v_mov_b32_e32 v69, v33
	v_lshl_add_u64 v[84:85], v[84:85], 0, v[32:33]
	v_cvt_pk_bf16_f32 v70, v70, v71
	v_cvt_pk_bf16_f32 v71, v72, v73
	v_lshl_add_u64 v[72:73], v[76:77], 0, s[56:57]
	v_lshl_add_u64 v[68:69], s[18:19], 0, v[68:69]
	global_store_dwordx2 v[84:85], v[78:79], off offset:96
	v_lshl_add_u64 v[78:79], v[76:77], 0, s[20:21]
	v_lshl_add_u64 v[72:73], v[72:73], 0, s[20:21]
	v_lshl_add_u64 v[68:69], v[68:69], 0, s[20:21]
	v_lshl_add_u64 v[78:79], v[78:79], 0, v[32:33]
	v_lshl_add_u64 v[72:73], v[72:73], 0, v[32:33]
	v_lshl_add_u64 v[68:69], v[68:69], 0, v[32:33]
	global_store_dwordx2 v[78:79], v[74:75], off offset:96
	global_store_dwordx2 v[72:73], v[70:71], off offset:96
	global_store_dwordx2 v[68:69], v[66:67], off offset:96
.LBB0_1063:
	s_add_i32 s17, s16, 0xffff8080
	s_add_i32 s18, s16, 0x80
	s_lshr_b32 s22, s17, 12
	s_add_i32 s22, s22, 4
	s_ashr_i32 s17, s18, 13
	s_cmp_gt_i32 s18, 0x1813f
	s_cbranch_scc1 .LBB0_1072
	s_ashr_i32 s19, s18, 31
	v_mov_b64_e32 v[66:67], v[198:199]
	v_mov_b64_e32 v[68:69], v[200:201]
	v_mov_b64_e32 v[70:71], v[216:217]
	v_mov_b64_e32 v[72:73], v[218:219]
	s_cmp_lt_i32 s18, 0x8000
	s_mov_b64 s[20:21], -1
	s_cbranch_scc1 .LBB0_1081
	s_cmp_lt_u32 s18, 0x18000
	s_cbranch_scc1 .LBB0_1067
	s_add_i32 s19, s16, 0xfffe8080
	s_lshr_b32 s23, s19, 4
	s_mov_b64 s[20:21], 0

; __device__ __forceinline__ float ss_rinv(u64 v) { return __builtin_amdgcn_rsqf((float)v * SS_INV + 1e-6f); }
;     __device__ __forceinline__ void operator()(const f32x4 (&acc)[2][2][4][2], const pg8::Unit& u, int wr, int wc, int fr, int fq) const {
;     ...
;                 const int row0 = u.pm * 256 + ai * 128 + wr * 64 + m * 16;
;                 if (row0 >= MREAL) continue;
;                 const u64x2 s01 = *(const u64x2*)(rowss + row0 + 4 * fq), s23 = *(const u64x2*)(rowss + row0 + 4 * fq + 2);
;                 f32x4 ri; ri[0] = ss_rinv(s01[0]); ri[1] = ss_rinv(s01[1]); ri[2] = ss_rinv(s23[0]); ri[3] = ss_rinv(s23[1]);
.LBB0_1073:
	s_ashr_i32 s19, s18, 31
	v_mov_b64_e32 v[50:51], v[220:221]
	v_mov_b64_e32 v[52:53], v[222:223]
	v_mov_b64_e32 v[54:55], v[224:225]
	v_mov_b64_e32 v[56:57], v[226:227]
	s_cmp_lt_i32 s18, 0x8000
	s_mov_b64 s[20:21], -1
	s_cbranch_scc1 .LBB0_1095
	s_cmp_lt_u32 s18, 0x18000
	s_cbranch_scc1 .LBB0_1076
	s_add_i32 s19, s16, 0xfffe8090
	s_lshr_b32 s23, s19, 4
	s_mov_b64 s[20:21], 0

; __device__ __forceinline__ float ss_rinv(u64 v) { return __builtin_amdgcn_rsqf((float)v * SS_INV + 1e-6f); }
; __device__ __forceinline__ unsigned cvtpk(float lo, float hi) { f32x2 v = {lo, hi}; bf16x2_t b = __builtin_convertvector(v, bf16x2_t); return __builtin_bit_cast(unsigned, b); }
;     __device__ __forceinline__ void operator()(const f32x4 (&acc)[2][2][4][2], const pg8::Unit& u, int wr, int wc, int fr, int fq) const {
;     ...
;                 const u64x2 s01 = *(const u64x2*)(rowss + row0 + 4 * fq), s23 = *(const u64x2*)(rowss + row0 + 4 * fq + 2);
;                 f32x4 ri; ri[0] = ss_rinv(s01[0]); ri[1] = ss_rinv(s01[1]); ri[2] = ss_rinv(s23[0]); ri[3] = ss_rinv(s23[1]);
;                 int s, p0, L; row_decode(row0, s, p0, L);
;                 const size_t so = seq_off_ch(s); const int LS = seq_LS(s);
; #pragma unroll
;                 for (int bj = 0; bj < 2; ++bj)
; #pragma unroll
;                     for (int n = 0; n < 2; ++n) {
;                         const int col = u.pn * 256 + bj * 128 + wc * 32 + n * 16 + fr;
;                         const int part = col >> 10, ch = col & 1023;
;                         const f32x4 v = acc[ai][bj][m][n] * ri;
;                         u32x2 w; w.x = cvtpk(v[0], v[1]); w.y = cvtpk(v[2], v[3]);
;                         *(u32x2*)(XT + (size_t)part * REGION + so + (size_t)ch * LS + XPAD + p0 + 4 * fq) = w;
;                     }
.LBB0_1085:
	v_ffbh_u32_e32 v32, v71
	v_min_u32_e32 v32, 32, v32
	v_lshlrev_b64 v[70:71], v32, v[70:71]
	v_min_u32_e32 v70, 1, v70
	v_or_b32_e32 v70, v71, v70
	v_cvt_f32_u32_e32 v70, v70
	v_ffbh_u32_e32 v71, v73
	v_sub_u32_e32 v32, 32, v32
	v_min_u32_e32 v71, 32, v71
	v_ldexp_f32 v32, v70, v32
	v_fmamk_f32 v32, v32, 0x30800000, v203
	v_lshlrev_b64 v[72:73], v71, v[72:73]
	v_rsq_f32_e32 v70, v32
	v_min_u32_e32 v32, 1, v72
	v_ffbh_u32_e32 v72, v67
	v_min_u32_e32 v72, 32, v72
	v_lshlrev_b64 v[66:67], v72, v[66:67]
	v_min_u32_e32 v66, 1, v66
	v_or_b32_e32 v32, v73, v32
	v_or_b32_e32 v66, v67, v66
	v_cvt_f32_u32_e32 v32, v32
	v_cvt_f32_u32_e32 v66, v66
	v_sub_u32_e32 v71, 32, v71
	v_sub_u32_e32 v67, 32, v72
	v_ldexp_f32 v32, v32, v71
	v_ldexp_f32 v71, v66, v67
	v_ffbh_u32_e32 v66, v69
	v_min_u32_e32 v72, 32, v66
	v_lshlrev_b64 v[66:67], v72, v[68:69]
	v_min_u32_e32 v66, 1, v66
	v_or_b32_e32 v66, v67, v66
	v_cvt_f32_u32_e32 v67, v66
	v_sub_u32_e32 v68, 32, v72
	v_fmamk_f32 v32, v32, 0x30800000, v203
	v_fmamk_f32 v66, v71, 0x30800000, v203
	v_ldexp_f32 v67, v67, v68
	v_fmamk_f32 v67, v67, 0x30800000, v203
	v_rsq_f32_e32 v66, v66
	v_rsq_f32_e32 v67, v67
	v_rsq_f32_e32 v71, v32
	s_add_u32 s21, s39, s11
	s_addc_u32 s23, s40, s9
	s_lshl_b64 s[18:19], s[18:19], 1
	s_add_u32 s18, s21, s18
	v_mul_u32_u24_e32 v72, s20, v164
	v_pk_mul_f32 v[64:65], v[64:65], v[66:67]
	v_pk_mul_f32 v[62:63], v[62:63], v[70:71]
	s_addc_u32 s19, s23, s19
	v_lshlrev_b32_e32 v32, 1, v72
	v_cvt_pk_bf16_f32 v62, v62, v63
	v_cvt_pk_bf16_f32 v63, v64, v65
	v_lshl_add_u64 v[64:65], s[18:19], 0, v[32:33]
	s_lshl_b64 s[24:25], s[56:57], 1
	v_pk_mul_f32 v[60:61], v[60:61], v[66:67]
	v_pk_mul_f32 v[58:59], v[58:59], v[70:71]
	s_lshl_b32 s21, s20, 4
	s_lshl_b32 s56, s20, 5
	s_mulk_i32 s20, 0x70
	v_cvt_pk_bf16_f32 v58, v58, v59
	v_cvt_pk_bf16_f32 v59, v60, v61
	v_lshl_add_u64 v[60:61], v[64:65], 0, s[56:57]
	s_lshl_b32 s56, s20, 1
	s_add_i32 s20, s21, s20
	v_pk_mul_f32 v[52:53], v[52:53], v[66:67]
	v_pk_mul_f32 v[50:51], v[50:51], v[70:71]
	s_add_i32 s20, s20, s21
	v_lshl_add_u64 v[68:69], v[64:65], 0, s[24:25]
	v_lshlrev_b32_e32 v32, 1, v142
	v_pk_mul_f32 v[56:57], v[56:57], v[66:67]
	v_pk_mul_f32 v[54:55], v[54:55], v[70:71]
	v_cvt_pk_bf16_f32 v50, v50, v51
	v_cvt_pk_bf16_f32 v51, v52, v53
	v_add_lshl_u32 v52, s20, v72, 1
	v_mov_b32_e32 v53, v33
	v_lshl_add_u64 v[68:69], v[68:69], 0, v[32:33]
	v_cvt_pk_bf16_f32 v54, v54, v55
	v_cvt_pk_bf16_f32 v55, v56, v57
	v_lshl_add_u64 v[56:57], v[60:61], 0, s[56:57]
	v_lshl_add_u64 v[52:53], s[18:19], 0, v[52:53]
	global_store_dwordx2 v[68:69], v[62:63], off offset:96
	v_lshl_add_u64 v[62:63], v[60:61], 0, s[24:25]
	v_lshl_add_u64 v[56:57], v[56:57], 0, s[24:25]
	v_lshl_add_u64 v[52:53], v[52:53], 0, s[24:25]
	v_lshl_add_u64 v[62:63], v[62:63], 0, v[32:33]
	v_lshl_add_u64 v[56:57], v[56:57], 0, v[32:33]
	v_lshl_add_u64 v[52:53], v[52:53], 0, v[32:33]
	global_store_dwordx2 v[62:63], v[58:59], off offset:96
	global_store_dwordx2 v[56:57], v[54:55], off offset:96
	global_store_dwordx2 v[52:53], v[50:51], off offset:96
	s_add_i32 s18, s16, 0x90
	s_cmp_gt_i32 s18, 0x1813f
	s_cbranch_scc0 .LBB0_1073

; __device__ __forceinline__ float ss_rinv(u64 v) { return __builtin_amdgcn_rsqf((float)v * SS_INV + 1e-6f); }
;     __device__ __forceinline__ void operator()(const f32x4 (&acc)[2][2][4][2], const pg8::Unit& u, int wr, int wc, int fr, int fq) const {
;     ...
;                 const int row0 = u.pm * 256 + ai * 128 + wr * 64 + m * 16;
;                 if (row0 >= MREAL) continue;
;                 const u64x2 s01 = *(const u64x2*)(rowss + row0 + 4 * fq), s23 = *(const u64x2*)(rowss + row0 + 4 * fq + 2);
;                 f32x4 ri; ri[0] = ss_rinv(s01[0]); ri[1] = ss_rinv(s01[1]); ri[2] = ss_rinv(s23[0]); ri[3] = ss_rinv(s23[1]);
.LBB0_1087:
	s_ashr_i32 s19, s18, 31
	v_mov_b64_e32 v[34:35], v[228:229]
	v_mov_b64_e32 v[36:37], v[230:231]
	v_mov_b64_e32 v[38:39], v[232:233]
	v_mov_b64_e32 v[40:41], v[234:235]
	s_cmp_lt_i32 s18, 0x8000
	s_mov_b64 s[20:21], -1
	s_cbranch_scc1 .LBB0_1109
	s_cmp_lt_u32 s18, 0x18000
	s_cbranch_scc1 .LBB0_1090
	s_add_i32 s19, s16, 0xfffe80a0
	s_lshr_b32 s23, s19, 4
	s_mov_b64 s[20:21], 0

; __device__ __forceinline__ float ss_rinv(u64 v) { return __builtin_amdgcn_rsqf((float)v * SS_INV + 1e-6f); }
; __device__ __forceinline__ unsigned cvtpk(float lo, float hi) { f32x2 v = {lo, hi}; bf16x2_t b = __builtin_convertvector(v, bf16x2_t); return __builtin_bit_cast(unsigned, b); }
;     __device__ __forceinline__ void operator()(const f32x4 (&acc)[2][2][4][2], const pg8::Unit& u, int wr, int wc, int fr, int fq) const {
;     ...
;                 const u64x2 s01 = *(const u64x2*)(rowss + row0 + 4 * fq), s23 = *(const u64x2*)(rowss + row0 + 4 * fq + 2);
;                 f32x4 ri; ri[0] = ss_rinv(s01[0]); ri[1] = ss_rinv(s01[1]); ri[2] = ss_rinv(s23[0]); ri[3] = ss_rinv(s23[1]);
;                 int s, p0, L; row_decode(row0, s, p0, L);
;                 const size_t so = seq_off_ch(s); const int LS = seq_LS(s);
; #pragma unroll
;                 for (int bj = 0; bj < 2; ++bj)
; #pragma unroll
;                     for (int n = 0; n < 2; ++n) {
;                         const int col = u.pn * 256 + bj * 128 + wc * 32 + n * 16 + fr;
;                         const int part = col >> 10, ch = col & 1023;
;                         const f32x4 v = acc[ai][bj][m][n] * ri;
;                         u32x2 w; w.x = cvtpk(v[0], v[1]); w.y = cvtpk(v[2], v[3]);
;                         *(u32x2*)(XT + (size_t)part * REGION + so + (size_t)ch * LS + XPAD + p0 + 4 * fq) = w;
;                     }
.LBB0_1099:
	v_ffbh_u32_e32 v32, v55
	v_min_u32_e32 v32, 32, v32
	v_lshlrev_b64 v[54:55], v32, v[54:55]
	v_min_u32_e32 v54, 1, v54
	v_or_b32_e32 v54, v55, v54
	v_cvt_f32_u32_e32 v54, v54
	v_ffbh_u32_e32 v55, v57
	v_sub_u32_e32 v32, 32, v32
	v_min_u32_e32 v55, 32, v55
	v_ldexp_f32 v32, v54, v32
	v_fmamk_f32 v32, v32, 0x30800000, v203
	v_lshlrev_b64 v[56:57], v55, v[56:57]
	v_rsq_f32_e32 v54, v32
	v_min_u32_e32 v32, 1, v56
	v_ffbh_u32_e32 v56, v51
	v_min_u32_e32 v56, 32, v56
	v_lshlrev_b64 v[50:51], v56, v[50:51]
	v_min_u32_e32 v50, 1, v50
	v_or_b32_e32 v32, v57, v32
	v_or_b32_e32 v50, v51, v50
	v_cvt_f32_u32_e32 v32, v32
	v_cvt_f32_u32_e32 v50, v50
	v_sub_u32_e32 v55, 32, v55
	v_sub_u32_e32 v51, 32, v56
	v_ldexp_f32 v32, v32, v55
	v_ldexp_f32 v55, v50, v51
	v_ffbh_u32_e32 v50, v53
	v_min_u32_e32 v56, 32, v50
	v_lshlrev_b64 v[50:51], v56, v[52:53]
	v_min_u32_e32 v50, 1, v50
	v_or_b32_e32 v50, v51, v50
	v_cvt_f32_u32_e32 v51, v50
	v_sub_u32_e32 v52, 32, v56
	v_fmamk_f32 v32, v32, 0x30800000, v203
	v_fmamk_f32 v50, v55, 0x30800000, v203
	v_ldexp_f32 v51, v51, v52
	v_fmamk_f32 v51, v51, 0x30800000, v203
	v_rsq_f32_e32 v50, v50
	v_rsq_f32_e32 v51, v51
	v_rsq_f32_e32 v55, v32
	s_add_u32 s21, s39, s11
	s_addc_u32 s23, s40, s9
	s_lshl_b64 s[18:19], s[18:19], 1
	s_add_u32 s18, s21, s18
	v_mul_u32_u24_e32 v56, s20, v164
	v_pk_mul_f32 v[48:49], v[48:49], v[50:51]
	v_pk_mul_f32 v[46:47], v[46:47], v[54:55]
	s_addc_u32 s19, s23, s19
	v_lshlrev_b32_e32 v32, 1, v56
	v_cvt_pk_bf16_f32 v46, v46, v47
	v_cvt_pk_bf16_f32 v47, v48, v49
	v_lshl_add_u64 v[48:49], s[18:19], 0, v[32:33]
	s_lshl_b64 s[24:25], s[56:57], 1
	v_pk_mul_f32 v[44:45], v[44:45], v[50:51]
	v_pk_mul_f32 v[42:43], v[42:43], v[54:55]
	s_lshl_b32 s21, s20, 4
	s_lshl_b32 s56, s20, 5
	s_mulk_i32 s20, 0x70
	v_cvt_pk_bf16_f32 v42, v42, v43
	v_cvt_pk_bf16_f32 v43, v44, v45
	v_lshl_add_u64 v[44:45], v[48:49], 0, s[56:57]
	s_lshl_b32 s56, s20, 1
	s_add_i32 s20, s21, s20
	v_pk_mul_f32 v[36:37], v[36:37], v[50:51]
	v_pk_mul_f32 v[34:35], v[34:35], v[54:55]
	s_add_i32 s20, s20, s21
	v_lshl_add_u64 v[52:53], v[48:49], 0, s[24:25]
	v_lshlrev_b32_e32 v32, 1, v142
	v_pk_mul_f32 v[40:41], v[40:41], v[50:51]
	v_pk_mul_f32 v[38:39], v[38:39], v[54:55]
	v_cvt_pk_bf16_f32 v34, v34, v35
	v_cvt_pk_bf16_f32 v35, v36, v37
	v_add_lshl_u32 v36, s20, v56, 1
	v_mov_b32_e32 v37, v33
	v_lshl_add_u64 v[52:53], v[52:53], 0, v[32:33]
	v_cvt_pk_bf16_f32 v38, v38, v39
	v_cvt_pk_bf16_f32 v39, v40, v41
	v_lshl_add_u64 v[40:41], v[44:45], 0, s[56:57]
	v_lshl_add_u64 v[36:37], s[18:19], 0, v[36:37]
	global_store_dwordx2 v[52:53], v[46:47], off offset:96
	v_lshl_add_u64 v[46:47], v[44:45], 0, s[24:25]
	v_lshl_add_u64 v[40:41], v[40:41], 0, s[24:25]
	v_lshl_add_u64 v[36:37], v[36:37], 0, s[24:25]
	v_lshl_add_u64 v[46:47], v[46:47], 0, v[32:33]
	v_lshl_add_u64 v[40:41], v[40:41], 0, v[32:33]
	v_lshl_add_u64 v[36:37], v[36:37], 0, v[32:33]
	global_store_dwordx2 v[46:47], v[42:43], off offset:96
	global_store_dwordx2 v[40:41], v[38:39], off offset:96
	global_store_dwordx2 v[36:37], v[34:35], off offset:96
	s_add_i32 s18, s16, 0xa0
	s_cmp_gt_i32 s18, 0x1813f
	s_cbranch_scc0 .LBB0_1087

; __device__ __forceinline__ float ss_rinv(u64 v) { return __builtin_amdgcn_rsqf((float)v * SS_INV + 1e-6f); }
;     __device__ __forceinline__ void operator()(const f32x4 (&acc)[2][2][4][2], const pg8::Unit& u, int wr, int wc, int fr, int fq) const {
;     ...
;                 const int row0 = u.pm * 256 + ai * 128 + wr * 64 + m * 16;
;                 if (row0 >= MREAL) continue;
;                 const u64x2 s01 = *(const u64x2*)(rowss + row0 + 4 * fq), s23 = *(const u64x2*)(rowss + row0 + 4 * fq + 2);
;                 f32x4 ri; ri[0] = ss_rinv(s01[0]); ri[1] = ss_rinv(s01[1]); ri[2] = ss_rinv(s23[0]); ri[3] = ss_rinv(s23[1]);
.LBB0_1101:
	s_ashr_i32 s19, s18, 31
	v_mov_b64_e32 v[16:17], v[146:147]
	v_mov_b64_e32 v[18:19], v[148:149]
	v_mov_b64_e32 v[20:21], v[236:237]
	v_mov_b64_e32 v[22:23], v[238:239]
	s_cmp_lt_i32 s18, 0x8000
	s_mov_b64 s[20:21], -1
	s_cbranch_scc1 .LBB0_1115
	s_cmp_lt_u32 s18, 0x18000
	s_cbranch_scc1 .LBB0_1104
	s_add_i32 s16, s16, 0xfffe80b0
	s_lshr_b32 s23, s16, 4
	s_mov_b64 s[20:21], 0

; __device__ __forceinline__ float ss_rinv(u64 v) { return __builtin_amdgcn_rsqf((float)v * SS_INV + 1e-6f); }
; __device__ __forceinline__ unsigned cvtpk(float lo, float hi) { f32x2 v = {lo, hi}; bf16x2_t b = __builtin_convertvector(v, bf16x2_t); return __builtin_bit_cast(unsigned, b); }
;     __device__ __forceinline__ void operator()(const f32x4 (&acc)[2][2][4][2], const pg8::Unit& u, int wr, int wc, int fr, int fq) const {
;     ...
;                 const u64x2 s01 = *(const u64x2*)(rowss + row0 + 4 * fq), s23 = *(const u64x2*)(rowss + row0 + 4 * fq + 2);
;                 f32x4 ri; ri[0] = ss_rinv(s01[0]); ri[1] = ss_rinv(s01[1]); ri[2] = ss_rinv(s23[0]); ri[3] = ss_rinv(s23[1]);
;                 int s, p0, L; row_decode(row0, s, p0, L);
;                 const size_t so = seq_off_ch(s); const int LS = seq_LS(s);
; #pragma unroll
;                 for (int bj = 0; bj < 2; ++bj)
; #pragma unroll
;                     for (int n = 0; n < 2; ++n) {
;                         const int col = u.pn * 256 + bj * 128 + wc * 32 + n * 16 + fr;
;                         const int part = col >> 10, ch = col & 1023;
;                         const f32x4 v = acc[ai][bj][m][n] * ri;
;                         u32x2 w; w.x = cvtpk(v[0], v[1]); w.y = cvtpk(v[2], v[3]);
;                         *(u32x2*)(XT + (size_t)part * REGION + so + (size_t)ch * LS + XPAD + p0 + 4 * fq) = w;
;                     }
.LBB0_1113:
	v_ffbh_u32_e32 v32, v39
	v_min_u32_e32 v32, 32, v32
	v_lshlrev_b64 v[38:39], v32, v[38:39]
	v_min_u32_e32 v38, 1, v38
	v_or_b32_e32 v38, v39, v38
	v_cvt_f32_u32_e32 v38, v38
	v_ffbh_u32_e32 v39, v41
	v_sub_u32_e32 v32, 32, v32
	v_min_u32_e32 v39, 32, v39
	v_ldexp_f32 v32, v38, v32
	v_fmamk_f32 v32, v32, 0x30800000, v203
	v_lshlrev_b64 v[40:41], v39, v[40:41]
	v_rsq_f32_e32 v38, v32
	v_min_u32_e32 v32, 1, v40
	v_ffbh_u32_e32 v40, v35
	v_min_u32_e32 v40, 32, v40
	v_lshlrev_b64 v[34:35], v40, v[34:35]
	v_min_u32_e32 v34, 1, v34
	v_or_b32_e32 v32, v41, v32
	v_or_b32_e32 v34, v35, v34
	v_cvt_f32_u32_e32 v32, v32
	v_cvt_f32_u32_e32 v34, v34
	v_sub_u32_e32 v39, 32, v39
	v_sub_u32_e32 v35, 32, v40
	v_ldexp_f32 v32, v32, v39
	v_ldexp_f32 v39, v34, v35
	v_ffbh_u32_e32 v34, v37
	v_min_u32_e32 v40, 32, v34
	v_lshlrev_b64 v[34:35], v40, v[36:37]
	v_min_u32_e32 v34, 1, v34
	v_or_b32_e32 v34, v35, v34
	v_cvt_f32_u32_e32 v35, v34
	v_sub_u32_e32 v36, 32, v40
	v_fmamk_f32 v32, v32, 0x30800000, v203
	v_fmamk_f32 v34, v39, 0x30800000, v203
	v_ldexp_f32 v35, v35, v36
	v_fmamk_f32 v35, v35, 0x30800000, v203
	v_rsq_f32_e32 v34, v34
	v_rsq_f32_e32 v35, v35
	v_rsq_f32_e32 v39, v32
	s_add_u32 s21, s39, s11
	s_addc_u32 s23, s40, s9
	s_lshl_b64 s[18:19], s[18:19], 1
	s_add_u32 s18, s21, s18
	v_mul_u32_u24_e32 v40, s20, v164
	v_pk_mul_f32 v[30:31], v[30:31], v[34:35]
	v_pk_mul_f32 v[28:29], v[28:29], v[38:39]
	s_addc_u32 s19, s23, s19
	v_lshlrev_b32_e32 v32, 1, v40
	v_cvt_pk_bf16_f32 v28, v28, v29
	v_cvt_pk_bf16_f32 v29, v30, v31
	v_lshl_add_u64 v[30:31], s[18:19], 0, v[32:33]
	s_lshl_b64 s[24:25], s[56:57], 1
	v_pk_mul_f32 v[26:27], v[26:27], v[34:35]
	v_pk_mul_f32 v[24:25], v[24:25], v[38:39]
	s_lshl_b32 s21, s20, 4
	s_lshl_b32 s56, s20, 5
	s_mulk_i32 s20, 0x70
	v_cvt_pk_bf16_f32 v24, v24, v25
	v_cvt_pk_bf16_f32 v25, v26, v27
	v_lshl_add_u64 v[26:27], v[30:31], 0, s[56:57]
	s_lshl_b32 s56, s20, 1
	s_add_i32 s20, s21, s20
	v_pk_mul_f32 v[18:19], v[18:19], v[34:35]
	v_pk_mul_f32 v[16:17], v[16:17], v[38:39]
	s_add_i32 s20, s20, s21
	v_lshl_add_u64 v[36:37], v[30:31], 0, s[24:25]
	v_lshlrev_b32_e32 v32, 1, v142
	v_pk_mul_f32 v[22:23], v[22:23], v[34:35]
	v_pk_mul_f32 v[20:21], v[20:21], v[38:39]
	v_cvt_pk_bf16_f32 v16, v16, v17
	v_cvt_pk_bf16_f32 v17, v18, v19
	v_add_lshl_u32 v18, s20, v40, 1
	v_mov_b32_e32 v19, v33
	v_lshl_add_u64 v[36:37], v[36:37], 0, v[32:33]
	v_cvt_pk_bf16_f32 v20, v20, v21
	v_cvt_pk_bf16_f32 v21, v22, v23
	v_lshl_add_u64 v[22:23], v[26:27], 0, s[56:57]
	v_lshl_add_u64 v[18:19], s[18:19], 0, v[18:19]
	global_store_dwordx2 v[36:37], v[28:29], off offset:96
	v_lshl_add_u64 v[28:29], v[26:27], 0, s[24:25]
	v_lshl_add_u64 v[22:23], v[22:23], 0, s[24:25]
	v_lshl_add_u64 v[18:19], v[18:19], 0, s[24:25]
	v_lshl_add_u64 v[28:29], v[28:29], 0, v[32:33]
	v_lshl_add_u64 v[22:23], v[22:23], 0, v[32:33]
	v_lshl_add_u64 v[18:19], v[18:19], 0, v[32:33]
	global_store_dwordx2 v[28:29], v[24:25], off offset:96
	global_store_dwordx2 v[22:23], v[20:21], off offset:96
	global_store_dwordx2 v[18:19], v[16:17], off offset:96
	s_add_i32 s18, s16, 0xb0
	s_cmp_gt_i32 s18, 0x1813f
	s_cbranch_scc0 .LBB0_1101

; __device__ __forceinline__ float ss_rinv(u64 v) { return __builtin_amdgcn_rsqf((float)v * SS_INV + 1e-6f); }
; __device__ __forceinline__ unsigned cvtpk(float lo, float hi) { f32x2 v = {lo, hi}; bf16x2_t b = __builtin_convertvector(v, bf16x2_t); return __builtin_bit_cast(unsigned, b); }
;     __device__ __forceinline__ void operator()(const f32x4 (&acc)[2][2][4][2], const pg8::Unit& u, int wr, int wc, int fr, int fq) const {
;     ...
;                 const u64x2 s01 = *(const u64x2*)(rowss + row0 + 4 * fq), s23 = *(const u64x2*)(rowss + row0 + 4 * fq + 2);
;                 f32x4 ri; ri[0] = ss_rinv(s01[0]); ri[1] = ss_rinv(s01[1]); ri[2] = ss_rinv(s23[0]); ri[3] = ss_rinv(s23[1]);
;                 int s, p0, L; row_decode(row0, s, p0, L);
;                 const size_t so = seq_off_ch(s); const int LS = seq_LS(s);
; #pragma unroll
;                 for (int bj = 0; bj < 2; ++bj)
; #pragma unroll
;                     for (int n = 0; n < 2; ++n) {
;                         const int col = u.pn * 256 + bj * 128 + wc * 32 + n * 16 + fr;
;                         const int part = col >> 10, ch = col & 1023;
;                         const f32x4 v = acc[ai][bj][m][n] * ri;
;                         u32x2 w; w.x = cvtpk(v[0], v[1]); w.y = cvtpk(v[2], v[3]);
;                         *(u32x2*)(XT + (size_t)part * REGION + so + (size_t)ch * LS + XPAD + p0 + 4 * fq) = w;
;                     }
.LBB0_1119:
	v_ffbh_u32_e32 v24, v21
	v_min_u32_e32 v24, 32, v24
	v_lshlrev_b64 v[20:21], v24, v[20:21]
	v_min_u32_e32 v20, 1, v20
	v_or_b32_e32 v20, v21, v20
	v_ffbh_u32_e32 v21, v23
	v_min_u32_e32 v21, 32, v21
	v_lshlrev_b64 v[22:23], v21, v[22:23]
	v_min_u32_e32 v22, 1, v22
	v_or_b32_e32 v22, v23, v22
	v_ffbh_u32_e32 v23, v17
	v_min_u32_e32 v23, 32, v23
	v_lshlrev_b64 v[16:17], v23, v[16:17]
	v_cvt_f32_u32_e32 v22, v22
	v_min_u32_e32 v16, 1, v16
	v_or_b32_e32 v16, v17, v16
	v_cvt_f32_u32_e32 v16, v16
	v_sub_u32_e32 v21, 32, v21
	v_ldexp_f32 v17, v22, v21
	v_fmamk_f32 v21, v17, 0x30800000, v203
	v_sub_u32_e32 v17, 32, v23
	v_ldexp_f32 v22, v16, v17
	v_ffbh_u32_e32 v16, v19
	v_min_u32_e32 v23, 32, v16
	v_lshlrev_b64 v[16:17], v23, v[18:19]
	v_min_u32_e32 v16, 1, v16
	v_or_b32_e32 v16, v17, v16
	v_cvt_f32_u32_e32 v20, v20
	v_cvt_f32_u32_e32 v17, v16
	v_sub_u32_e32 v24, 32, v24
	v_sub_u32_e32 v18, 32, v23
	v_ldexp_f32 v20, v20, v24
	v_ldexp_f32 v17, v17, v18
	v_fmamk_f32 v20, v20, 0x30800000, v203
	v_fmamk_f32 v16, v22, 0x30800000, v203
	v_fmamk_f32 v17, v17, 0x30800000, v203
	v_rsq_f32_e32 v20, v20
	v_rsq_f32_e32 v16, v16
	v_rsq_f32_e32 v17, v17
	v_rsq_f32_e32 v21, v21
	s_add_u32 s11, s39, s11
	s_addc_u32 s9, s40, s9
	s_lshl_b64 s[16:17], s[16:17], 1
	s_add_u32 s16, s11, s16
	v_mul_u32_u24_e32 v22, s18, v164
	v_pk_mul_f32 v[14:15], v[14:15], v[16:17]
	v_pk_mul_f32 v[12:13], v[12:13], v[20:21]
	s_addc_u32 s17, s9, s17
	v_lshlrev_b32_e32 v32, 1, v22
	v_cvt_pk_bf16_f32 v12, v12, v13
	v_cvt_pk_bf16_f32 v13, v14, v15
	v_lshl_add_u64 v[14:15], s[16:17], 0, v[32:33]
	s_lshl_b64 s[20:21], s[56:57], 1
	v_pk_mul_f32 v[10:11], v[10:11], v[16:17]
	v_pk_mul_f32 v[8:9], v[8:9], v[20:21]
	s_lshl_b32 s9, s18, 4
	s_lshl_b32 s56, s18, 5
	s_mul_i32 s11, s18, 0x70
	v_cvt_pk_bf16_f32 v8, v8, v9
	v_cvt_pk_bf16_f32 v9, v10, v11
	v_lshl_add_u64 v[10:11], v[14:15], 0, s[56:57]
	s_lshl_b32 s56, s11, 1
	s_add_i32 s11, s9, s11
	v_pk_mul_f32 v[2:3], v[2:3], v[16:17]
	v_pk_mul_f32 v[0:1], v[0:1], v[20:21]
	s_add_i32 s11, s11, s9
	v_lshl_add_u64 v[18:19], v[14:15], 0, s[20:21]
	v_lshlrev_b32_e32 v32, 1, v142
	v_pk_mul_f32 v[6:7], v[6:7], v[16:17]
	v_pk_mul_f32 v[4:5], v[4:5], v[20:21]
	v_cvt_pk_bf16_f32 v0, v0, v1
	v_cvt_pk_bf16_f32 v1, v2, v3
	v_add_lshl_u32 v2, s11, v22, 1
	v_mov_b32_e32 v3, v33
	v_lshl_add_u64 v[18:19], v[18:19], 0, v[32:33]
	v_cvt_pk_bf16_f32 v4, v4, v5
	v_cvt_pk_bf16_f32 v5, v6, v7
	v_lshl_add_u64 v[6:7], v[10:11], 0, s[56:57]
	v_lshl_add_u64 v[2:3], s[16:17], 0, v[2:3]
	global_store_dwordx2 v[18:19], v[12:13], off offset:96
	v_lshl_add_u64 v[12:13], v[10:11], 0, s[20:21]
	v_lshl_add_u64 v[6:7], v[6:7], 0, s[20:21]
	v_lshl_add_u64 v[2:3], v[2:3], 0, s[20:21]
	v_lshl_add_u64 v[12:13], v[12:13], 0, v[32:33]
	v_lshl_add_u64 v[6:7], v[6:7], 0, v[32:33]
	v_lshl_add_u64 v[2:3], v[2:3], 0, v[32:33]
	global_store_dwordx2 v[12:13], v[8:9], off offset:96
	global_store_dwordx2 v[6:7], v[4:5], off offset:96
	global_store_dwordx2 v[2:3], v[0:1], off offset:96
	s_andn2_b64 vcc, exec, s[2:3]
	s_mov_b64 s[2:3], -1
	s_cbranch_vccnz .LBB0_1000
